# w3 loop with at most 15 outstanding LDS ops (safety variant of previous)
# baseline (speedup 1.0000x reference)
; __device__ __forceinline__ void filter_item(const Params& p, int l, int Lf, int t0, float* dst, float* hidT  , int wid0) {
;     ...
; #pragma unroll 16
;     for (int j = 0; j < 64; ++j) {
;         const float wa = w3[j * 1024 + tid], wb = w3[j * 1024 + 512 + tid];
; #pragma unroll
;         for (int g = 0; g < 8; ++g) { const f32x4 hv = *(const f32x4*)(hidT + j * 32 + 4 * g);
; #pragma unroll
;             for (int i = 0; i < 4; ++i) { acc0[4 * g + i] += hv[i] * wa; acc1[4 * g + i] += hv[i] * wb; } }
;     }
.Lw3_719_loop:
	ds_read_b128 v[142:145], v186 offset:128
	ds_read_b128 v[146:149], v186 offset:144
	ds_read_b128 v[150:153], v186 offset:160
	ds_read_b128 v[154:157], v186 offset:176
	ds_read_b128 v[158:161], v186 offset:192
	ds_read_b128 v[162:165], v186 offset:208
	ds_read_b128 v[166:169], v186 offset:224
	s_waitcnt vmcnt(2) lgkmcnt(7)
	ds_read_b128 v[170:173], v186 offset:240
	v_pk_fma_f32 v[68:69], v[174:175], v[110:111], v[68:69] op_sel_hi:[0,1,1]
	v_pk_fma_f32 v[62:63], v[176:177], v[110:111], v[62:63] op_sel_hi:[0,1,1]
	v_pk_fma_f32 v[66:67], v[174:175], v[112:113], v[66:67] op_sel_hi:[0,1,1]
	v_pk_fma_f32 v[64:65], v[176:177], v[112:113], v[64:65] op_sel_hi:[0,1,1]
	v_pk_fma_f32 v[60:61], v[174:175], v[114:115], v[60:61] op_sel_hi:[0,1,1]
	v_pk_fma_f32 v[56:57], v[176:177], v[114:115], v[56:57] op_sel_hi:[0,1,1]
	v_pk_fma_f32 v[58:59], v[174:175], v[116:117], v[58:59] op_sel_hi:[0,1,1]
	v_pk_fma_f32 v[54:55], v[176:177], v[116:117], v[54:55] op_sel_hi:[0,1,1]
	v_pk_fma_f32 v[52:53], v[174:175], v[118:119], v[52:53] op_sel_hi:[0,1,1]
	v_pk_fma_f32 v[48:49], v[176:177], v[118:119], v[48:49] op_sel_hi:[0,1,1]
	v_pk_fma_f32 v[50:51], v[174:175], v[120:121], v[50:51] op_sel_hi:[0,1,1]
	v_pk_fma_f32 v[46:47], v[176:177], v[120:121], v[46:47] op_sel_hi:[0,1,1]
	v_pk_fma_f32 v[44:45], v[174:175], v[122:123], v[44:45] op_sel_hi:[0,1,1]
	v_pk_fma_f32 v[40:41], v[176:177], v[122:123], v[40:41] op_sel_hi:[0,1,1]
	v_pk_fma_f32 v[42:43], v[174:175], v[124:125], v[42:43] op_sel_hi:[0,1,1]
	v_pk_fma_f32 v[38:39], v[176:177], v[124:125], v[38:39] op_sel_hi:[0,1,1]
	v_pk_fma_f32 v[36:37], v[174:175], v[126:127], v[36:37] op_sel_hi:[0,1,1]
	v_pk_fma_f32 v[32:33], v[176:177], v[126:127], v[32:33] op_sel_hi:[0,1,1]
	v_pk_fma_f32 v[34:35], v[174:175], v[128:129], v[34:35] op_sel_hi:[0,1,1]
	v_pk_fma_f32 v[30:31], v[176:177], v[128:129], v[30:31] op_sel_hi:[0,1,1]
	v_pk_fma_f32 v[28:29], v[174:175], v[130:131], v[28:29] op_sel_hi:[0,1,1]
	v_pk_fma_f32 v[24:25], v[176:177], v[130:131], v[24:25] op_sel_hi:[0,1,1]
	v_pk_fma_f32 v[26:27], v[174:175], v[132:133], v[26:27] op_sel_hi:[0,1,1]
	v_pk_fma_f32 v[22:23], v[176:177], v[132:133], v[22:23] op_sel_hi:[0,1,1]
	v_pk_fma_f32 v[20:21], v[174:175], v[134:135], v[20:21] op_sel_hi:[0,1,1]
	v_pk_fma_f32 v[14:15], v[176:177], v[134:135], v[14:15] op_sel_hi:[0,1,1]
	v_pk_fma_f32 v[18:19], v[174:175], v[136:137], v[18:19] op_sel_hi:[0,1,1]
	v_pk_fma_f32 v[16:17], v[176:177], v[136:137], v[16:17] op_sel_hi:[0,1,1]
	v_pk_fma_f32 v[10:11], v[174:175], v[138:139], v[10:11] op_sel_hi:[0,1,1]
	v_pk_fma_f32 v[6:7], v[176:177], v[138:139], v[6:7] op_sel_hi:[0,1,1]
	v_pk_fma_f32 v[12:13], v[174:175], v[140:141], v[12:13] op_sel_hi:[0,1,1]
	v_pk_fma_f32 v[8:9], v[176:177], v[140:141], v[8:9] op_sel_hi:[0,1,1]
	global_load_dword v174, v[182:183], off
	global_load_dword v176, v[182:183], off offset:2048
	v_lshl_add_u64 v[182:183], v[182:183], 0, vcc
	ds_read_b128 v[110:113], v186 offset:256
	ds_read_b128 v[114:117], v186 offset:272
	ds_read_b128 v[118:121], v186 offset:288
	ds_read_b128 v[122:125], v186 offset:304
	ds_read_b128 v[126:129], v186 offset:320
	ds_read_b128 v[130:133], v186 offset:336
	ds_read_b128 v[134:137], v186 offset:352
	s_waitcnt vmcnt(2) lgkmcnt(7)
	ds_read_b128 v[138:141], v186 offset:368
	v_pk_fma_f32 v[68:69], v[178:179], v[142:143], v[68:69] op_sel_hi:[0,1,1]
	v_pk_fma_f32 v[62:63], v[180:181], v[142:143], v[62:63] op_sel_hi:[0,1,1]
	v_pk_fma_f32 v[66:67], v[178:179], v[144:145], v[66:67] op_sel_hi:[0,1,1]
	v_pk_fma_f32 v[64:65], v[180:181], v[144:145], v[64:65] op_sel_hi:[0,1,1]
	v_pk_fma_f32 v[60:61], v[178:179], v[146:147], v[60:61] op_sel_hi:[0,1,1]
	v_pk_fma_f32 v[56:57], v[180:181], v[146:147], v[56:57] op_sel_hi:[0,1,1]
	v_pk_fma_f32 v[58:59], v[178:179], v[148:149], v[58:59] op_sel_hi:[0,1,1]
	v_pk_fma_f32 v[54:55], v[180:181], v[148:149], v[54:55] op_sel_hi:[0,1,1]
	v_pk_fma_f32 v[52:53], v[178:179], v[150:151], v[52:53] op_sel_hi:[0,1,1]
	v_pk_fma_f32 v[48:49], v[180:181], v[150:151], v[48:49] op_sel_hi:[0,1,1]
	v_pk_fma_f32 v[50:51], v[178:179], v[152:153], v[50:51] op_sel_hi:[0,1,1]
	v_pk_fma_f32 v[46:47], v[180:181], v[152:153], v[46:47] op_sel_hi:[0,1,1]
	v_pk_fma_f32 v[44:45], v[178:179], v[154:155], v[44:45] op_sel_hi:[0,1,1]
	v_pk_fma_f32 v[40:41], v[180:181], v[154:155], v[40:41] op_sel_hi:[0,1,1]
	v_pk_fma_f32 v[42:43], v[178:179], v[156:157], v[42:43] op_sel_hi:[0,1,1]
	v_pk_fma_f32 v[38:39], v[180:181], v[156:157], v[38:39] op_sel_hi:[0,1,1]
	v_pk_fma_f32 v[36:37], v[178:179], v[158:159], v[36:37] op_sel_hi:[0,1,1]
	v_pk_fma_f32 v[32:33], v[180:181], v[158:159], v[32:33] op_sel_hi:[0,1,1]
	v_pk_fma_f32 v[34:35], v[178:179], v[160:161], v[34:35] op_sel_hi:[0,1,1]
	v_pk_fma_f32 v[30:31], v[180:181], v[160:161], v[30:31] op_sel_hi:[0,1,1]
	v_pk_fma_f32 v[28:29], v[178:179], v[162:163], v[28:29] op_sel_hi:[0,1,1]
	v_pk_fma_f32 v[24:25], v[180:181], v[162:163], v[24:25] op_sel_hi:[0,1,1]
	v_pk_fma_f32 v[26:27], v[178:179], v[164:165], v[26:27] op_sel_hi:[0,1,1]
	v_pk_fma_f32 v[22:23], v[180:181], v[164:165], v[22:23] op_sel_hi:[0,1,1]
	v_pk_fma_f32 v[20:21], v[178:179], v[166:167], v[20:21] op_sel_hi:[0,1,1]
	v_pk_fma_f32 v[14:15], v[180:181], v[166:167], v[14:15] op_sel_hi:[0,1,1]
	v_pk_fma_f32 v[18:19], v[178:179], v[168:169], v[18:19] op_sel_hi:[0,1,1]
	v_pk_fma_f32 v[16:17], v[180:181], v[168:169], v[16:17] op_sel_hi:[0,1,1]
	v_pk_fma_f32 v[10:11], v[178:179], v[170:171], v[10:11] op_sel_hi:[0,1,1]
	v_pk_fma_f32 v[6:7], v[180:181], v[170:171], v[6:7] op_sel_hi:[0,1,1]
	v_pk_fma_f32 v[12:13], v[178:179], v[172:173], v[12:13] op_sel_hi:[0,1,1]
	v_pk_fma_f32 v[8:9], v[180:181], v[172:173], v[8:9] op_sel_hi:[0,1,1]
	global_load_dword v178, v[182:183], off
	global_load_dword v180, v[182:183], off offset:2048
	v_lshl_add_u64 v[182:183], v[182:183], 0, vcc
	v_add_u32_e32 v186, 0x100, v186
	s_add_i32 s1, s1, -1
	s_cmp_lg_u32 s1, 0
	s_cbranch_scc1 .Lw3_719_loop
; __device__ __forceinline__ void filter_item(const Params& p, int l, int Lf, int t0, float* dst, float* hidT  , int wid0) {
;     ...
; #pragma unroll 16
;     for (int j = 0; j < 64; ++j) {
;         const float wa = w3[j * 1024 + tid], wb = w3[j * 1024 + 512 + tid];
; #pragma unroll
;         for (int g = 0; g < 8; ++g) { const f32x4 hv = *(const f32x4*)(hidT + j * 32 + 4 * g);
; #pragma unroll
;             for (int i = 0; i < 4; ++i) { acc0[4 * g + i] += hv[i] * wa; acc1[4 * g + i] += hv[i] * wb; } }
;     }
;     const float dmin = -3.0701134573253945f, dmax = -15.350567286626973f;
;     const float delta = fabsf(dmin + (float)tid * ((dmax - dmin) / 511.f));
; #pragma unroll
;     for (int g = 0; g < 8; ++g) { f32x4 o0, o1;
; #pragma unroll
;         for (int i = 0; i < 4; ++i) { const float tn = (float)(t0 + 4 * g + i) / (float)(Lf - 1); const float wdw = __expf(-tn * delta); o0[i] = acc0[4 * g + i] * wdw; o1[i] = acc1[4 * g + i] * wdw; }
	ds_read_b128 v[142:145], v186 offset:128
	ds_read_b128 v[146:149], v186 offset:144
	ds_read_b128 v[150:153], v186 offset:160
	ds_read_b128 v[154:157], v186 offset:176
	ds_read_b128 v[158:161], v186 offset:192
	ds_read_b128 v[162:165], v186 offset:208
	ds_read_b128 v[166:169], v186 offset:224
	s_waitcnt vmcnt(2) lgkmcnt(7)
	ds_read_b128 v[170:173], v186 offset:240
	v_pk_fma_f32 v[68:69], v[174:175], v[110:111], v[68:69] op_sel_hi:[0,1,1]
	v_pk_fma_f32 v[62:63], v[176:177], v[110:111], v[62:63] op_sel_hi:[0,1,1]
	v_pk_fma_f32 v[66:67], v[174:175], v[112:113], v[66:67] op_sel_hi:[0,1,1]
	v_pk_fma_f32 v[64:65], v[176:177], v[112:113], v[64:65] op_sel_hi:[0,1,1]
	v_pk_fma_f32 v[60:61], v[174:175], v[114:115], v[60:61] op_sel_hi:[0,1,1]
	v_pk_fma_f32 v[56:57], v[176:177], v[114:115], v[56:57] op_sel_hi:[0,1,1]
	v_pk_fma_f32 v[58:59], v[174:175], v[116:117], v[58:59] op_sel_hi:[0,1,1]
	v_pk_fma_f32 v[54:55], v[176:177], v[116:117], v[54:55] op_sel_hi:[0,1,1]
	v_pk_fma_f32 v[52:53], v[174:175], v[118:119], v[52:53] op_sel_hi:[0,1,1]
	v_pk_fma_f32 v[48:49], v[176:177], v[118:119], v[48:49] op_sel_hi:[0,1,1]
	v_pk_fma_f32 v[50:51], v[174:175], v[120:121], v[50:51] op_sel_hi:[0,1,1]
	v_pk_fma_f32 v[46:47], v[176:177], v[120:121], v[46:47] op_sel_hi:[0,1,1]
	v_pk_fma_f32 v[44:45], v[174:175], v[122:123], v[44:45] op_sel_hi:[0,1,1]
	v_pk_fma_f32 v[40:41], v[176:177], v[122:123], v[40:41] op_sel_hi:[0,1,1]
	v_pk_fma_f32 v[42:43], v[174:175], v[124:125], v[42:43] op_sel_hi:[0,1,1]
	v_pk_fma_f32 v[38:39], v[176:177], v[124:125], v[38:39] op_sel_hi:[0,1,1]
	v_pk_fma_f32 v[36:37], v[174:175], v[126:127], v[36:37] op_sel_hi:[0,1,1]
	v_pk_fma_f32 v[32:33], v[176:177], v[126:127], v[32:33] op_sel_hi:[0,1,1]
	v_pk_fma_f32 v[34:35], v[174:175], v[128:129], v[34:35] op_sel_hi:[0,1,1]
	v_pk_fma_f32 v[30:31], v[176:177], v[128:129], v[30:31] op_sel_hi:[0,1,1]
	v_pk_fma_f32 v[28:29], v[174:175], v[130:131], v[28:29] op_sel_hi:[0,1,1]
	v_pk_fma_f32 v[24:25], v[176:177], v[130:131], v[24:25] op_sel_hi:[0,1,1]
	v_pk_fma_f32 v[26:27], v[174:175], v[132:133], v[26:27] op_sel_hi:[0,1,1]
	v_pk_fma_f32 v[22:23], v[176:177], v[132:133], v[22:23] op_sel_hi:[0,1,1]
	v_pk_fma_f32 v[20:21], v[174:175], v[134:135], v[20:21] op_sel_hi:[0,1,1]
	v_pk_fma_f32 v[14:15], v[176:177], v[134:135], v[14:15] op_sel_hi:[0,1,1]
	v_pk_fma_f32 v[18:19], v[174:175], v[136:137], v[18:19] op_sel_hi:[0,1,1]
	v_pk_fma_f32 v[16:17], v[176:177], v[136:137], v[16:17] op_sel_hi:[0,1,1]
	v_pk_fma_f32 v[10:11], v[174:175], v[138:139], v[10:11] op_sel_hi:[0,1,1]
	v_pk_fma_f32 v[6:7], v[176:177], v[138:139], v[6:7] op_sel_hi:[0,1,1]
	v_pk_fma_f32 v[12:13], v[174:175], v[140:141], v[12:13] op_sel_hi:[0,1,1]
	v_pk_fma_f32 v[8:9], v[176:177], v[140:141], v[8:9] op_sel_hi:[0,1,1]
	s_waitcnt vmcnt(0) lgkmcnt(0)
	v_pk_fma_f32 v[68:69], v[178:179], v[142:143], v[68:69] op_sel_hi:[0,1,1]
	v_pk_fma_f32 v[62:63], v[180:181], v[142:143], v[62:63] op_sel_hi:[0,1,1]
	v_pk_fma_f32 v[66:67], v[178:179], v[144:145], v[66:67] op_sel_hi:[0,1,1]
	v_pk_fma_f32 v[64:65], v[180:181], v[144:145], v[64:65] op_sel_hi:[0,1,1]
	v_pk_fma_f32 v[60:61], v[178:179], v[146:147], v[60:61] op_sel_hi:[0,1,1]
	v_pk_fma_f32 v[56:57], v[180:181], v[146:147], v[56:57] op_sel_hi:[0,1,1]
	v_pk_fma_f32 v[58:59], v[178:179], v[148:149], v[58:59] op_sel_hi:[0,1,1]
	v_pk_fma_f32 v[54:55], v[180:181], v[148:149], v[54:55] op_sel_hi:[0,1,1]
	v_pk_fma_f32 v[52:53], v[178:179], v[150:151], v[52:53] op_sel_hi:[0,1,1]
	v_pk_fma_f32 v[48:49], v[180:181], v[150:151], v[48:49] op_sel_hi:[0,1,1]
	v_pk_fma_f32 v[50:51], v[178:179], v[152:153], v[50:51] op_sel_hi:[0,1,1]
	v_pk_fma_f32 v[46:47], v[180:181], v[152:153], v[46:47] op_sel_hi:[0,1,1]
	v_pk_fma_f32 v[44:45], v[178:179], v[154:155], v[44:45] op_sel_hi:[0,1,1]
	v_pk_fma_f32 v[40:41], v[180:181], v[154:155], v[40:41] op_sel_hi:[0,1,1]
	v_pk_fma_f32 v[42:43], v[178:179], v[156:157], v[42:43] op_sel_hi:[0,1,1]
	v_pk_fma_f32 v[38:39], v[180:181], v[156:157], v[38:39] op_sel_hi:[0,1,1]
	v_pk_fma_f32 v[36:37], v[178:179], v[158:159], v[36:37] op_sel_hi:[0,1,1]
	v_pk_fma_f32 v[32:33], v[180:181], v[158:159], v[32:33] op_sel_hi:[0,1,1]
	v_pk_fma_f32 v[34:35], v[178:179], v[160:161], v[34:35] op_sel_hi:[0,1,1]
	v_pk_fma_f32 v[30:31], v[180:181], v[160:161], v[30:31] op_sel_hi:[0,1,1]
	v_pk_fma_f32 v[28:29], v[178:179], v[162:163], v[28:29] op_sel_hi:[0,1,1]
	v_pk_fma_f32 v[24:25], v[180:181], v[162:163], v[24:25] op_sel_hi:[0,1,1]
	v_pk_fma_f32 v[26:27], v[178:179], v[164:165], v[26:27] op_sel_hi:[0,1,1]
	v_pk_fma_f32 v[22:23], v[180:181], v[164:165], v[22:23] op_sel_hi:[0,1,1]
	v_pk_fma_f32 v[20:21], v[178:179], v[166:167], v[20:21] op_sel_hi:[0,1,1]
	v_pk_fma_f32 v[14:15], v[180:181], v[166:167], v[14:15] op_sel_hi:[0,1,1]
	v_pk_fma_f32 v[18:19], v[178:179], v[168:169], v[18:19] op_sel_hi:[0,1,1]
	v_pk_fma_f32 v[16:17], v[180:181], v[168:169], v[16:17] op_sel_hi:[0,1,1]
	v_pk_fma_f32 v[10:11], v[178:179], v[170:171], v[10:11] op_sel_hi:[0,1,1]
	v_pk_fma_f32 v[6:7], v[180:181], v[170:171], v[6:7] op_sel_hi:[0,1,1]
	v_pk_fma_f32 v[12:13], v[178:179], v[172:173], v[12:13] op_sel_hi:[0,1,1]
	v_pk_fma_f32 v[8:9], v[180:181], v[172:173], v[8:9] op_sel_hi:[0,1,1]
	s_mov_b32 s0, 0
	v_add_u32_e32 v4, 0x10000, v4
	v_cvt_f32_i32_e32 v5, s74
	s_mov_b32 s6, 0xc5fff800
	v_ashrrev_i32_e32 v3, 31, v2
	v_readlane_b32 s4, v252, 32
	v_div_scale_f32 v70, s[38:39], s6, s6, v5
	v_rcp_f32_e32 v71, v70
	v_cvt_f32_i32_e32 v4, v0
	v_lshlrev_b64 v[0:1], 15, v[0:1]
	v_readlane_b32 s5, v252, 33
	v_fma_f32 v72, -v70, v71, 1.0
	s_ashr_i32 s75, s74, 31
	v_lshlrev_b64 v[2:3], 15, v[2:3]
	v_fmac_f32_e32 v71, v72, v71
	v_div_scale_f32 v72, vcc, v5, s6, v5
; __device__ __forceinline__ void filter_item(const Params& p, int l, int Lf, int t0, float* dst, float* hidT  , int wid0) {
;     ...
;     const float dmin = -3.0701134573253945f, dmax = -15.350567286626973f;
;     const float delta = fabsf(dmin + (float)tid * ((dmax - dmin) / 511.f));
; #pragma unroll
;     for (int g = 0; g < 8; ++g) { f32x4 o0, o1;
; #pragma unroll
;         for (int i = 0; i < 4; ++i) { const float tn = (float)(t0 + 4 * g + i) / (float)(Lf - 1); const float wdw = __expf(-tn * delta); o0[i] = acc0[4 * g + i] * wdw; o1[i] = acc1[4 * g + i] * wdw; }
;         *(f32x4*)(dst + (size_t)tid * Lf + t0 + 4 * g) = o0; *(f32x4*)(dst + (size_t)(512 + tid) * Lf + t0 + 4 * g) = o1; }
	v_lshl_add_u64 v[0:1], s[4:5], 0, v[0:1]
	s_lshl_b64 s[0:1], s[74:75], 2
	v_lshl_add_u64 v[2:3], s[4:5], 0, v[2:3]
	v_mul_f32_e32 v73, v72, v71
	v_lshl_add_u64 v[0:1], v[0:1], 0, s[0:1]
	v_lshl_add_u64 v[2:3], v[2:3], 0, s[0:1]
	v_fma_f32 v74, -v70, v73, v72
	s_or_b32 s0, s74, 1
	v_fmac_f32_e32 v73, v74, v71
	v_cvt_f32_i32_e32 v74, s0
	v_fma_f32 v70, -v70, v73, v72
	v_div_fmas_f32 v70, v70, v71, v73
	v_div_fixup_f32 v5, v70, s6, v5
	v_div_scale_f32 v70, s[0:1], s6, s6, v74
	v_rcp_f32_e32 v71, v70
	v_fmamk_f32 v4, v4, 0xbcc4df2d, v219
	v_mul_f32_e64 v5, v5, |v4|
	v_mul_f32_e32 v5, 0x3fb8aa3b, v5
	v_exp_f32_e32 v72, v5
	v_fma_f32 v5, -v70, v71, 1.0
	v_fmac_f32_e32 v71, v5, v71
	v_div_scale_f32 v5, vcc, v74, s6, v74
	v_mul_f32_e32 v73, v5, v71
	v_fma_f32 v75, -v70, v73, v5
	v_fmac_f32_e32 v73, v75, v71
	s_or_b32 s0, s74, 2
	v_fma_f32 v5, -v70, v73, v5
	v_cvt_f32_i32_e32 v70, s0
	v_div_fmas_f32 v5, v5, v71, v73
	v_div_fixup_f32 v5, v5, s6, v74
	v_mul_f32_e64 v5, v5, |v4|
	v_div_scale_f32 v71, s[0:1], s6, s6, v70
	v_rcp_f32_e32 v74, v71
	v_mul_f32_e32 v5, 0x3fb8aa3b, v5
	v_exp_f32_e32 v73, v5
	s_or_b32 s0, s74, 3
	v_fma_f32 v5, -v71, v74, 1.0
	v_fmac_f32_e32 v74, v5, v74
	v_div_scale_f32 v5, vcc, v70, s6, v70
	v_mul_f32_e32 v75, v5, v74
	v_fma_f32 v76, -v71, v75, v5
	v_fmac_f32_e32 v75, v76, v74
	v_fma_f32 v5, -v71, v75, v5
	v_cvt_f32_i32_e32 v71, s0
	v_div_fmas_f32 v5, v5, v74, v75
	v_div_fixup_f32 v5, v5, s6, v70
	v_mul_f32_e64 v5, v5, |v4|
	v_div_scale_f32 v70, s[0:1], s6, s6, v71
	v_rcp_f32_e32 v75, v70
	v_mul_f32_e32 v5, 0x3fb8aa3b, v5
	v_exp_f32_e32 v74, v5
	s_or_b32 s0, s74, 4
	v_fma_f32 v5, -v70, v75, 1.0
	v_fmac_f32_e32 v75, v5, v75
	v_div_scale_f32 v5, vcc, v71, s6, v71
	v_mul_f32_e32 v76, v5, v75
	v_fma_f32 v77, -v70, v76, v5
	v_fmac_f32_e32 v76, v77, v75
	v_fma_f32 v5, -v70, v76, v5
	v_div_fmas_f32 v5, v5, v75, v76
	v_div_fixup_f32 v5, v5, s6, v71
	v_mul_f32_e64 v5, v5, |v4|
	v_mul_f32_e32 v5, 0x3fb8aa3b, v5
	v_exp_f32_e32 v75, v5
	v_cvt_f32_i32_e32 v5, s0
	v_pk_mul_f32 v[68:69], v[72:73], v[68:69]
	v_pk_mul_f32 v[62:63], v[72:73], v[62:63]
	v_pk_mul_f32 v[70:71], v[74:75], v[66:67]
	v_div_scale_f32 v66, s[0:1], s6, s6, v5
	v_rcp_f32_e32 v67, v66
	v_pk_mul_f32 v[64:65], v[74:75], v[64:65]
	global_store_dwordx4 v[0:1], v[68:71], off
	global_store_dwordx4 v[2:3], v[62:65], off
	s_or_b32 s0, s74, 5
	s_add_i32 s26, s26, s24
	v_fma_f32 v62, -v66, v67, 1.0
	v_fmac_f32_e32 v67, v62, v67
	v_div_scale_f32 v62, vcc, v5, s6, v5
	v_mul_f32_e32 v63, v62, v67
	v_fma_f32 v64, -v66, v63, v62
	v_cvt_f32_i32_e32 v65, s0
	v_fmac_f32_e32 v63, v64, v67
	v_fma_f32 v62, -v66, v63, v62
	v_div_fmas_f32 v62, v62, v67, v63
	v_div_fixup_f32 v5, v62, s6, v5
	v_div_scale_f32 v62, s[0:1], s6, s6, v65
	v_rcp_f32_e32 v63, v62
	v_mul_f32_e64 v5, v5, |v4|
	v_mul_f32_e32 v5, 0x3fb8aa3b, v5
	v_exp_f32_e32 v64, v5
	v_fma_f32 v5, -v62, v63, 1.0
	v_fmac_f32_e32 v63, v5, v63
	v_div_scale_f32 v5, vcc, v65, s6, v65
	v_mul_f32_e32 v66, v5, v63
	v_fma_f32 v67, -v62, v66, v5
	v_fmac_f32_e32 v66, v67, v63
	s_or_b32 s0, s74, 6
	v_fma_f32 v5, -v62, v66, v5
	v_cvt_f32_i32_e32 v62, s0
	v_div_fmas_f32 v5, v5, v63, v66
	v_div_fixup_f32 v5, v5, s6, v65
	v_mul_f32_e64 v5, v5, |v4|
	v_div_scale_f32 v63, s[0:1], s6, s6, v62
	v_rcp_f32_e32 v66, v63
	v_mul_f32_e32 v5, 0x3fb8aa3b, v5
	v_exp_f32_e32 v65, v5
	s_or_b32 s0, s74, 7
	v_fma_f32 v5, -v63, v66, 1.0
	v_fmac_f32_e32 v66, v5, v66
	v_div_scale_f32 v5, vcc, v62, s6, v62
	v_mul_f32_e32 v67, v5, v66
	v_fma_f32 v68, -v63, v67, v5
	v_fmac_f32_e32 v67, v68, v66
	v_fma_f32 v5, -v63, v67, v5
	v_cvt_f32_i32_e32 v63, s0
	v_div_fmas_f32 v5, v5, v66, v67
	v_div_fixup_f32 v5, v5, s6, v62
	v_mul_f32_e64 v5, v5, |v4|
	v_div_scale_f32 v62, s[0:1], s6, s6, v63
	v_rcp_f32_e32 v67, v62
	v_mul_f32_e32 v5, 0x3fb8aa3b, v5
	v_exp_f32_e32 v66, v5
	s_or_b32 s0, s74, 8
	v_fma_f32 v5, -v62, v67, 1.0
	v_fmac_f32_e32 v67, v5, v67
	v_div_scale_f32 v5, vcc, v63, s6, v63
	v_mul_f32_e32 v68, v5, v67
	v_fma_f32 v69, -v62, v68, v5
	v_fmac_f32_e32 v68, v69, v67
	v_fma_f32 v5, -v62, v68, v5
	v_div_fmas_f32 v5, v5, v67, v68
	v_div_fixup_f32 v5, v5, s6, v63
	v_mul_f32_e64 v5, v5, |v4|
	v_mul_f32_e32 v5, 0x3fb8aa3b, v5
	v_exp_f32_e32 v67, v5
	v_cvt_f32_i32_e32 v5, s0
	v_pk_mul_f32 v[60:61], v[64:65], v[60:61]
	v_pk_mul_f32 v[56:57], v[64:65], v[56:57]
	v_pk_mul_f32 v[62:63], v[66:67], v[58:59]
	v_div_scale_f32 v64, s[0:1], s6, s6, v5
	v_rcp_f32_e32 v65, v64
	v_pk_mul_f32 v[58:59], v[66:67], v[54:55]
	s_or_b32 s0, s74, 9
	global_store_dwordx4 v[0:1], v[60:63], off offset:16
	global_store_dwordx4 v[2:3], v[56:59], off offset:16
	v_fma_f32 v54, -v64, v65, 1.0
	v_fmac_f32_e32 v65, v54, v65
	v_div_scale_f32 v54, vcc, v5, s6, v5
	v_mul_f32_e32 v55, v54, v65
	v_fma_f32 v56, -v64, v55, v54
	v_cvt_f32_i32_e32 v57, s0
	v_fmac_f32_e32 v55, v56, v65
	v_fma_f32 v54, -v64, v55, v54
	v_div_fmas_f32 v54, v54, v65, v55
	v_div_fixup_f32 v5, v54, s6, v5
	v_div_scale_f32 v54, s[0:1], s6, s6, v57
	v_rcp_f32_e32 v55, v54
	v_mul_f32_e64 v5, v5, |v4|
	v_mul_f32_e32 v5, 0x3fb8aa3b, v5
	v_exp_f32_e32 v56, v5
	v_fma_f32 v5, -v54, v55, 1.0
	v_fmac_f32_e32 v55, v5, v55
	v_div_scale_f32 v5, vcc, v57, s6, v57
	v_mul_f32_e32 v58, v5, v55
	v_fma_f32 v59, -v54, v58, v5
	v_fmac_f32_e32 v58, v59, v55
	s_or_b32 s0, s74, 10
	v_fma_f32 v5, -v54, v58, v5
	v_cvt_f32_i32_e32 v54, s0
	v_div_fmas_f32 v5, v5, v55, v58
	v_div_fixup_f32 v5, v5, s6, v57
	v_mul_f32_e64 v5, v5, |v4|
	v_div_scale_f32 v55, s[0:1], s6, s6, v54
	v_rcp_f32_e32 v58, v55
	v_mul_f32_e32 v5, 0x3fb8aa3b, v5
	v_exp_f32_e32 v57, v5
	s_or_b32 s0, s74, 11
	v_fma_f32 v5, -v55, v58, 1.0
	v_fmac_f32_e32 v58, v5, v58
	v_div_scale_f32 v5, vcc, v54, s6, v54
; __device__ __forceinline__ void filter_item(const Params& p, int l, int Lf, int t0, float* dst, float* hidT  , int wid0) {
;     ...
;     const float dmin = -3.0701134573253945f, dmax = -15.350567286626973f;
;     const float delta = fabsf(dmin + (float)tid * ((dmax - dmin) / 511.f));
; #pragma unroll
;     for (int g = 0; g < 8; ++g) { f32x4 o0, o1;
; #pragma unroll
;         for (int i = 0; i < 4; ++i) { const float tn = (float)(t0 + 4 * g + i) / (float)(Lf - 1); const float wdw = __expf(-tn * delta); o0[i] = acc0[4 * g + i] * wdw; o1[i] = acc1[4 * g + i] * wdw; }
;         *(f32x4*)(dst + (size_t)tid * Lf + t0 + 4 * g) = o0; *(f32x4*)(dst + (size_t)(512 + tid) * Lf + t0 + 4 * g) = o1; }
	v_mul_f32_e32 v59, v5, v58
	v_fma_f32 v60, -v55, v59, v5
	v_fmac_f32_e32 v59, v60, v58
	v_fma_f32 v5, -v55, v59, v5
	v_cvt_f32_i32_e32 v55, s0
	v_div_fmas_f32 v5, v5, v58, v59
	v_div_fixup_f32 v5, v5, s6, v54
	v_mul_f32_e64 v5, v5, |v4|
	v_div_scale_f32 v54, s[0:1], s6, s6, v55
	v_rcp_f32_e32 v59, v54
	v_mul_f32_e32 v5, 0x3fb8aa3b, v5
	v_exp_f32_e32 v58, v5
	s_or_b32 s0, s74, 12
	v_fma_f32 v5, -v54, v59, 1.0
	v_fmac_f32_e32 v59, v5, v59
	v_div_scale_f32 v5, vcc, v55, s6, v55
	v_mul_f32_e32 v60, v5, v59
	v_fma_f32 v61, -v54, v60, v5
	v_fmac_f32_e32 v60, v61, v59
	v_fma_f32 v5, -v54, v60, v5
	v_div_fmas_f32 v5, v5, v59, v60
	v_div_fixup_f32 v5, v5, s6, v55
	v_mul_f32_e64 v5, v5, |v4|
	v_mul_f32_e32 v5, 0x3fb8aa3b, v5
	v_exp_f32_e32 v59, v5
	v_cvt_f32_i32_e32 v5, s0
	v_pk_mul_f32 v[52:53], v[56:57], v[52:53]
	v_pk_mul_f32 v[48:49], v[56:57], v[48:49]
	v_pk_mul_f32 v[54:55], v[58:59], v[50:51]
	v_div_scale_f32 v56, s[0:1], s6, s6, v5
	v_rcp_f32_e32 v57, v56
	v_pk_mul_f32 v[50:51], v[58:59], v[46:47]
	s_or_b32 s0, s74, 13
	global_store_dwordx4 v[0:1], v[52:55], off offset:32
	global_store_dwordx4 v[2:3], v[48:51], off offset:32
	v_fma_f32 v46, -v56, v57, 1.0
	v_fmac_f32_e32 v57, v46, v57
	v_div_scale_f32 v46, vcc, v5, s6, v5
	v_mul_f32_e32 v47, v46, v57
	v_fma_f32 v48, -v56, v47, v46
	v_cvt_f32_i32_e32 v49, s0
	v_fmac_f32_e32 v47, v48, v57
	v_fma_f32 v46, -v56, v47, v46
	v_div_fmas_f32 v46, v46, v57, v47
	v_div_fixup_f32 v5, v46, s6, v5
	v_div_scale_f32 v46, s[0:1], s6, s6, v49
	v_rcp_f32_e32 v47, v46
	v_mul_f32_e64 v5, v5, |v4|
	v_mul_f32_e32 v5, 0x3fb8aa3b, v5
	v_exp_f32_e32 v48, v5
	v_fma_f32 v5, -v46, v47, 1.0
	v_fmac_f32_e32 v47, v5, v47
	v_div_scale_f32 v5, vcc, v49, s6, v49
	v_mul_f32_e32 v50, v5, v47
	v_fma_f32 v51, -v46, v50, v5
	v_fmac_f32_e32 v50, v51, v47
	s_or_b32 s0, s74, 14
	v_fma_f32 v5, -v46, v50, v5
	v_cvt_f32_i32_e32 v46, s0
	v_div_fmas_f32 v5, v5, v47, v50
	v_div_fixup_f32 v5, v5, s6, v49
	v_mul_f32_e64 v5, v5, |v4|
	v_div_scale_f32 v47, s[0:1], s6, s6, v46
	v_rcp_f32_e32 v50, v47
	v_mul_f32_e32 v5, 0x3fb8aa3b, v5
	v_exp_f32_e32 v49, v5
	s_or_b32 s0, s74, 15
	v_fma_f32 v5, -v47, v50, 1.0
	v_fmac_f32_e32 v50, v5, v50
	v_div_scale_f32 v5, vcc, v46, s6, v46
	v_mul_f32_e32 v51, v5, v50
	v_fma_f32 v52, -v47, v51, v5
	v_fmac_f32_e32 v51, v52, v50
	v_fma_f32 v5, -v47, v51, v5
	v_cvt_f32_i32_e32 v47, s0
	v_div_fmas_f32 v5, v5, v50, v51
	v_div_fixup_f32 v5, v5, s6, v46
	v_mul_f32_e64 v5, v5, |v4|
	v_div_scale_f32 v46, s[0:1], s6, s6, v47
	v_rcp_f32_e32 v51, v46
	v_mul_f32_e32 v5, 0x3fb8aa3b, v5
	v_exp_f32_e32 v50, v5
	s_or_b32 s0, s74, 16
	v_fma_f32 v5, -v46, v51, 1.0
	v_fmac_f32_e32 v51, v5, v51
	v_div_scale_f32 v5, vcc, v47, s6, v47
	v_mul_f32_e32 v52, v5, v51
	v_fma_f32 v53, -v46, v52, v5
	v_fmac_f32_e32 v52, v53, v51
	v_fma_f32 v5, -v46, v52, v5
	v_div_fmas_f32 v5, v5, v51, v52
	v_div_fixup_f32 v5, v5, s6, v47
	v_mul_f32_e64 v5, v5, |v4|
	v_mul_f32_e32 v5, 0x3fb8aa3b, v5
	v_exp_f32_e32 v51, v5
	v_cvt_f32_i32_e32 v5, s0
	v_pk_mul_f32 v[44:45], v[48:49], v[44:45]
	v_pk_mul_f32 v[40:41], v[48:49], v[40:41]
	v_pk_mul_f32 v[46:47], v[50:51], v[42:43]
	v_div_scale_f32 v48, s[0:1], s6, s6, v5
	v_rcp_f32_e32 v49, v48
	v_pk_mul_f32 v[42:43], v[50:51], v[38:39]
	s_or_b32 s0, s74, 17
	global_store_dwordx4 v[0:1], v[44:47], off offset:48
	global_store_dwordx4 v[2:3], v[40:43], off offset:48
	v_fma_f32 v38, -v48, v49, 1.0
	v_fmac_f32_e32 v49, v38, v49
	v_div_scale_f32 v38, vcc, v5, s6, v5
	v_mul_f32_e32 v39, v38, v49
	v_fma_f32 v40, -v48, v39, v38
	v_cvt_f32_i32_e32 v41, s0
	v_fmac_f32_e32 v39, v40, v49
	v_fma_f32 v38, -v48, v39, v38
	v_div_fmas_f32 v38, v38, v49, v39
	v_div_fixup_f32 v5, v38, s6, v5
	v_div_scale_f32 v38, s[0:1], s6, s6, v41
	v_rcp_f32_e32 v39, v38
	v_mul_f32_e64 v5, v5, |v4|
	v_mul_f32_e32 v5, 0x3fb8aa3b, v5
	v_exp_f32_e32 v40, v5
	v_fma_f32 v5, -v38, v39, 1.0
	v_fmac_f32_e32 v39, v5, v39
	v_div_scale_f32 v5, vcc, v41, s6, v41
	v_mul_f32_e32 v42, v5, v39
	v_fma_f32 v43, -v38, v42, v5
	v_fmac_f32_e32 v42, v43, v39
	s_or_b32 s0, s74, 18
	v_fma_f32 v5, -v38, v42, v5
	v_cvt_f32_i32_e32 v38, s0
	v_div_fmas_f32 v5, v5, v39, v42
	v_div_fixup_f32 v5, v5, s6, v41
	v_mul_f32_e64 v5, v5, |v4|
	v_div_scale_f32 v39, s[0:1], s6, s6, v38
	v_rcp_f32_e32 v42, v39
	v_mul_f32_e32 v5, 0x3fb8aa3b, v5
	v_exp_f32_e32 v41, v5
	s_or_b32 s0, s74, 19
	v_fma_f32 v5, -v39, v42, 1.0
	v_fmac_f32_e32 v42, v5, v42
	v_div_scale_f32 v5, vcc, v38, s6, v38
	v_mul_f32_e32 v43, v5, v42
	v_fma_f32 v44, -v39, v43, v5
	v_fmac_f32_e32 v43, v44, v42
	v_fma_f32 v5, -v39, v43, v5
	v_cvt_f32_i32_e32 v39, s0
	v_div_fmas_f32 v5, v5, v42, v43
	v_div_fixup_f32 v5, v5, s6, v38
	v_mul_f32_e64 v5, v5, |v4|
	v_div_scale_f32 v38, s[0:1], s6, s6, v39
	v_rcp_f32_e32 v43, v38
	v_mul_f32_e32 v5, 0x3fb8aa3b, v5
	v_exp_f32_e32 v42, v5
	s_or_b32 s0, s74, 20
	v_fma_f32 v5, -v38, v43, 1.0
	v_fmac_f32_e32 v43, v5, v43
	v_div_scale_f32 v5, vcc, v39, s6, v39
	v_mul_f32_e32 v44, v5, v43
	v_fma_f32 v45, -v38, v44, v5
	v_fmac_f32_e32 v44, v45, v43
	v_fma_f32 v5, -v38, v44, v5
	v_div_fmas_f32 v5, v5, v43, v44
	v_div_fixup_f32 v5, v5, s6, v39
	v_mul_f32_e64 v5, v5, |v4|
	v_mul_f32_e32 v5, 0x3fb8aa3b, v5
	v_exp_f32_e32 v43, v5
	v_cvt_f32_i32_e32 v5, s0
	v_pk_mul_f32 v[36:37], v[40:41], v[36:37]
	v_pk_mul_f32 v[32:33], v[40:41], v[32:33]
	v_pk_mul_f32 v[38:39], v[42:43], v[34:35]
	v_div_scale_f32 v40, s[0:1], s6, s6, v5
	v_rcp_f32_e32 v41, v40
	v_pk_mul_f32 v[34:35], v[42:43], v[30:31]
	s_or_b32 s0, s74, 21
	global_store_dwordx4 v[0:1], v[36:39], off offset:64
	global_store_dwordx4 v[2:3], v[32:35], off offset:64
	v_fma_f32 v30, -v40, v41, 1.0
	v_fmac_f32_e32 v41, v30, v41
; __device__ __forceinline__ void filter_item(const Params& p, int l, int Lf, int t0, float* dst, float* hidT  , int wid0) {
;     ...
;     const float dmin = -3.0701134573253945f, dmax = -15.350567286626973f;
;     const float delta = fabsf(dmin + (float)tid * ((dmax - dmin) / 511.f));
; #pragma unroll
;     for (int g = 0; g < 8; ++g) { f32x4 o0, o1;
; #pragma unroll
;         for (int i = 0; i < 4; ++i) { const float tn = (float)(t0 + 4 * g + i) / (float)(Lf - 1); const float wdw = __expf(-tn * delta); o0[i] = acc0[4 * g + i] * wdw; o1[i] = acc1[4 * g + i] * wdw; }
;         *(f32x4*)(dst + (size_t)tid * Lf + t0 + 4 * g) = o0; *(f32x4*)(dst + (size_t)(512 + tid) * Lf + t0 + 4 * g) = o1; }
;     __syncthreads();
; __device__ __forceinline__ void phaseA(const Params& p, int l, unsigned char* lds, int wid0) {
;     ...
;     { float* hidT = (float*)(lds + 104448);
;       for (int it = blockIdx.x; it < 256; it += gridDim.x) filter_item(p, l, SEQ, 32 * it, (float*)(ws + WS_FILT), hidT, wid0);
;       }
	v_div_scale_f32 v30, vcc, v5, s6, v5
	v_mul_f32_e32 v31, v30, v41
	v_fma_f32 v32, -v40, v31, v30
	v_cvt_f32_i32_e32 v33, s0
	v_fmac_f32_e32 v31, v32, v41
	v_fma_f32 v30, -v40, v31, v30
	v_div_fmas_f32 v30, v30, v41, v31
	v_div_fixup_f32 v5, v30, s6, v5
	v_div_scale_f32 v30, s[0:1], s6, s6, v33
	v_rcp_f32_e32 v31, v30
	v_mul_f32_e64 v5, v5, |v4|
	v_mul_f32_e32 v5, 0x3fb8aa3b, v5
	v_exp_f32_e32 v32, v5
	v_fma_f32 v5, -v30, v31, 1.0
	v_fmac_f32_e32 v31, v5, v31
	v_div_scale_f32 v5, vcc, v33, s6, v33
	v_mul_f32_e32 v34, v5, v31
	v_fma_f32 v35, -v30, v34, v5
	v_fmac_f32_e32 v34, v35, v31
	s_or_b32 s0, s74, 22
	v_fma_f32 v5, -v30, v34, v5
	v_cvt_f32_i32_e32 v30, s0
	v_div_fmas_f32 v5, v5, v31, v34
	v_div_fixup_f32 v5, v5, s6, v33
	v_mul_f32_e64 v5, v5, |v4|
	v_div_scale_f32 v31, s[0:1], s6, s6, v30
	v_rcp_f32_e32 v34, v31
	v_mul_f32_e32 v5, 0x3fb8aa3b, v5
	v_exp_f32_e32 v33, v5
	s_or_b32 s0, s74, 23
	v_fma_f32 v5, -v31, v34, 1.0
	v_fmac_f32_e32 v34, v5, v34
	v_div_scale_f32 v5, vcc, v30, s6, v30
	v_mul_f32_e32 v35, v5, v34
	v_fma_f32 v36, -v31, v35, v5
	v_fmac_f32_e32 v35, v36, v34
	v_fma_f32 v5, -v31, v35, v5
	v_cvt_f32_i32_e32 v31, s0
	v_div_fmas_f32 v5, v5, v34, v35
	v_div_fixup_f32 v5, v5, s6, v30
	v_mul_f32_e64 v5, v5, |v4|
	v_div_scale_f32 v30, s[0:1], s6, s6, v31
	v_rcp_f32_e32 v35, v30
	v_mul_f32_e32 v5, 0x3fb8aa3b, v5
	v_exp_f32_e32 v34, v5
	s_or_b32 s0, s74, 24
	v_fma_f32 v5, -v30, v35, 1.0
	v_fmac_f32_e32 v35, v5, v35
	v_div_scale_f32 v5, vcc, v31, s6, v31
	v_mul_f32_e32 v36, v5, v35
	v_fma_f32 v37, -v30, v36, v5
	v_fmac_f32_e32 v36, v37, v35
	v_fma_f32 v5, -v30, v36, v5
	v_div_fmas_f32 v5, v5, v35, v36
	v_div_fixup_f32 v5, v5, s6, v31
	v_mul_f32_e64 v5, v5, |v4|
	v_mul_f32_e32 v5, 0x3fb8aa3b, v5
	v_exp_f32_e32 v35, v5
	v_cvt_f32_i32_e32 v5, s0
	v_pk_mul_f32 v[28:29], v[32:33], v[28:29]
	v_pk_mul_f32 v[24:25], v[32:33], v[24:25]
	v_pk_mul_f32 v[30:31], v[34:35], v[26:27]
	v_div_scale_f32 v32, s[0:1], s6, s6, v5
	v_rcp_f32_e32 v33, v32
	v_pk_mul_f32 v[26:27], v[34:35], v[22:23]
	s_or_b32 s0, s74, 25
	global_store_dwordx4 v[0:1], v[28:31], off offset:80
	global_store_dwordx4 v[2:3], v[24:27], off offset:80
	v_fma_f32 v22, -v32, v33, 1.0
	v_fmac_f32_e32 v33, v22, v33
	v_div_scale_f32 v22, vcc, v5, s6, v5
	v_mul_f32_e32 v23, v22, v33
	v_fma_f32 v24, -v32, v23, v22
	v_cvt_f32_i32_e32 v25, s0
	v_fmac_f32_e32 v23, v24, v33
	v_fma_f32 v22, -v32, v23, v22
	v_div_fmas_f32 v22, v22, v33, v23
	v_div_fixup_f32 v5, v22, s6, v5
	v_div_scale_f32 v22, s[0:1], s6, s6, v25
	v_rcp_f32_e32 v23, v22
	v_mul_f32_e64 v5, v5, |v4|
	v_mul_f32_e32 v5, 0x3fb8aa3b, v5
	v_exp_f32_e32 v24, v5
	v_fma_f32 v5, -v22, v23, 1.0
	v_fmac_f32_e32 v23, v5, v23
	v_div_scale_f32 v5, vcc, v25, s6, v25
	v_mul_f32_e32 v26, v5, v23
	v_fma_f32 v27, -v22, v26, v5
	v_fmac_f32_e32 v26, v27, v23
	s_or_b32 s0, s74, 26
	v_fma_f32 v5, -v22, v26, v5
	v_cvt_f32_i32_e32 v22, s0
	v_div_fmas_f32 v5, v5, v23, v26
	v_div_fixup_f32 v5, v5, s6, v25
	v_mul_f32_e64 v5, v5, |v4|
	v_div_scale_f32 v23, s[0:1], s6, s6, v22
	v_rcp_f32_e32 v26, v23
	v_mul_f32_e32 v5, 0x3fb8aa3b, v5
	v_exp_f32_e32 v25, v5
	s_or_b32 s0, s74, 27
	v_fma_f32 v5, -v23, v26, 1.0
	v_fmac_f32_e32 v26, v5, v26
	v_div_scale_f32 v5, vcc, v22, s6, v22
	v_mul_f32_e32 v27, v5, v26
	v_fma_f32 v28, -v23, v27, v5
	v_fmac_f32_e32 v27, v28, v26
	v_fma_f32 v5, -v23, v27, v5
	v_cvt_f32_i32_e32 v23, s0
	v_div_fmas_f32 v5, v5, v26, v27
	v_div_fixup_f32 v5, v5, s6, v22
	v_mul_f32_e64 v5, v5, |v4|
	v_div_scale_f32 v22, s[0:1], s6, s6, v23
	v_rcp_f32_e32 v27, v22
	v_mul_f32_e32 v5, 0x3fb8aa3b, v5
	v_exp_f32_e32 v26, v5
	s_or_b32 s0, s74, 28
	v_fma_f32 v5, -v22, v27, 1.0
	v_fmac_f32_e32 v27, v5, v27
	v_div_scale_f32 v5, vcc, v23, s6, v23
	v_mul_f32_e32 v28, v5, v27
	v_fma_f32 v29, -v22, v28, v5
	v_fmac_f32_e32 v28, v29, v27
	v_fma_f32 v5, -v22, v28, v5
	v_div_fmas_f32 v5, v5, v27, v28
	v_cvt_f32_i32_e32 v28, s0
	v_div_fixup_f32 v5, v5, s6, v23
	v_mul_f32_e64 v5, v5, |v4|
	v_mul_f32_e32 v5, 0x3fb8aa3b, v5
	v_exp_f32_e32 v27, v5
	v_div_scale_f32 v5, s[0:1], s6, s6, v28
	v_rcp_f32_e32 v29, v5
	v_pk_mul_f32 v[22:23], v[26:27], v[18:19]
	v_pk_mul_f32 v[20:21], v[24:25], v[20:21]
	v_pk_mul_f32 v[14:15], v[24:25], v[14:15]
	v_fma_f32 v18, -v5, v29, 1.0
	v_fmac_f32_e32 v29, v18, v29
	v_div_scale_f32 v18, vcc, v28, s6, v28
	v_mul_f32_e32 v19, v18, v29
	v_fma_f32 v24, -v5, v19, v18
	s_or_b32 s0, s74, 29
	v_fmac_f32_e32 v19, v24, v29
	v_cvt_f32_i32_e32 v24, s0
	v_fma_f32 v5, -v5, v19, v18
	v_div_fmas_f32 v5, v5, v29, v19
	v_div_fixup_f32 v5, v5, s6, v28
	v_div_scale_f32 v19, s[0:1], s6, s6, v24
	v_rcp_f32_e32 v25, v19
	v_mul_f32_e64 v5, v5, |v4|
	v_mul_f32_e32 v5, 0x3fb8aa3b, v5
	v_exp_f32_e32 v18, v5
	v_fma_f32 v5, -v19, v25, 1.0
	v_fmac_f32_e32 v25, v5, v25
	v_div_scale_f32 v5, vcc, v24, s6, v24
	v_pk_mul_f32 v[16:17], v[26:27], v[16:17]
	v_mul_f32_e32 v26, v5, v25
	v_fma_f32 v27, -v19, v26, v5
	s_or_b32 s0, s74, 30
	v_fmac_f32_e32 v26, v27, v25
	v_cvt_f32_i32_e32 v27, s0
	v_fma_f32 v5, -v19, v26, v5
	v_div_fmas_f32 v5, v5, v25, v26
	v_div_fixup_f32 v5, v5, s6, v24
	v_div_scale_f32 v24, s[0:1], s6, s6, v27
	v_rcp_f32_e32 v25, v24
	v_mul_f32_e64 v5, v5, |v4|
	v_mul_f32_e32 v5, 0x3fb8aa3b, v5
	v_exp_f32_e32 v19, v5
	v_fma_f32 v5, -v24, v25, 1.0
	v_fmac_f32_e32 v25, v5, v25
	v_div_scale_f32 v5, vcc, v27, s6, v27
	v_mul_f32_e32 v26, v5, v25
	v_fma_f32 v28, -v24, v26, v5
	s_or_b32 s0, s74, 31
	v_fmac_f32_e32 v26, v28, v25
	v_cvt_f32_i32_e32 v28, s0
	v_fma_f32 v5, -v24, v26, v5
	v_div_fmas_f32 v5, v5, v25, v26
	v_div_fixup_f32 v5, v5, s6, v27
	v_div_scale_f32 v25, s[0:1], s6, s6, v28
	v_rcp_f32_e32 v26, v25
	v_mul_f32_e64 v5, v5, |v4|
	v_mul_f32_e32 v5, 0x3fb8aa3b, v5
	v_exp_f32_e32 v24, v5
	v_fma_f32 v5, -v25, v26, 1.0
	v_fmac_f32_e32 v26, v5, v26
	v_div_scale_f32 v5, vcc, v28, s6, v28
	v_mul_f32_e32 v27, v5, v26
	v_fma_f32 v29, -v25, v27, v5
	v_fmac_f32_e32 v27, v29, v26
	v_fma_f32 v5, -v25, v27, v5
	v_div_fmas_f32 v5, v5, v26, v27
	v_div_fixup_f32 v5, v5, s6, v28
	v_mul_f32_e64 v4, v5, |v4|
	v_mul_f32_e32 v4, 0x3fb8aa3b, v4
	v_exp_f32_e32 v25, v4
	v_pk_mul_f32 v[10:11], v[18:19], v[10:11]
	s_cmpk_gt_i32 s26, 0xff
	s_mov_b32 s75, 0x18000
	v_pk_mul_f32 v[12:13], v[24:25], v[12:13]
	global_store_dwordx4 v[0:1], v[20:23], off offset:96
	global_store_dwordx4 v[2:3], v[14:17], off offset:96
	v_pk_mul_f32 v[4:5], v[18:19], v[6:7]
	v_pk_mul_f32 v[6:7], v[24:25], v[8:9]
	global_store_dwordx4 v[0:1], v[10:13], off offset:112
	global_store_dwordx4 v[2:3], v[4:7], off offset:112
	s_barrier
	s_cbranch_scc0 .LBB0_592
	s_branch .LBB0_725
